# v1 plus padding: attention steady-loop head at 16 mod 64, later phases as v1 mod 64
# baseline (speedup 1.0000x reference)
; #define WAIT_BAR(N) asm volatile("s_waitcnt vmcnt(" #N ") lgkmcnt(0)\n\ts_barrier":::"memory")
;   #define DMA_K(t,slot) glds16(ksrc+(long)(t)*KVBLK*DM,(unsigned)__builtin_amdgcn_readfirstlane(kdst+(slot)))
;   #define DMA_V(t,slot) do{ glds16(vsrc+(long)(t)*KVBLK*DM,(unsigned)__builtin_amdgcn_readfirstlane(vdst+(slot))); glds16(vsrc+64+(long)(t)*KVBLK*DM,(unsigned)__builtin_amdgcn_readfirstlane(vdst2+(slot))); }while(0)
;   #define CMASK(P0,P1,t) do{int jb_=(t)-(NT-4); if(jb_>=0)cmask(P0,P1,jb_,qrel,hi);}while(0)
;   #define START(P0,P1) do{ resc=false; \
;     { _Pragma("unroll") for(int r=0;r<16;++r){P0[r]=fsub_s(P0[r],mhat);P1[r]=fsub_s(P1[r],mhat);} \
;       } \
;     _Pragma("unroll") for(int r=0;r<16;++r)P0[r]=__builtin_amdgcn_exp2f(P0[r]); }while(0)
;   #define ROT() do{sl_prev=sl_cur;sl_cur=sl_next;sl_next=(sl_next==(NSLOT-1)*SLOTB)?0:sl_next+SLOTB;}while(0)
;   #define CMASK(P0,P1,t) do{}while(0)
;   #define CMASK(P0,P1,t) do{int jb_=(t)-(NT-4); if(jb_>=0)cmask(P0,P1,jb_,qrel,hi);}while(0)
; template<int THRL> __device__ __forceinline__ void attn_unit(int b,int h,int qb,unsigned char*wsb,char*shm,float kmax,const int CMB,float lam){
;     ...
;   const float mhat=sqrtf(q2_)*kmax*1.004f+0.02f;
;   float l_reg=0.f;f32x16 o[2];o[0]=f32x16{};o[1]=f32x16{};f32x16 o2[2];o2[0]=f32x16{};o2[1]=f32x16{};const f32x16 negm=f32x16{};
;   const int qrel=wid*QBLK+r32;
;     ...
;   bool resc=false;
;     ...
;   f32x16 pA0,pA1,pB0,pB1;
;   int sl_prev=0,sl_cur=0,sl_next=SLOTB;
;     ...
;   DMA_K(2,2*SLOTB);
;   WAIT_BAR(4);
;   qkt(pA0,pA1,Kbase,qr,negm,r32,hi);asm volatile("s_nop 15\n\ts_nop 7":"+v"(pA0),"+v"(pA1));CMASK(pA0,pA1,0);
;   START(pA0,pA1);
;   _Pragma("unroll") for(int r=0;r<16;++r)pA1[r]=__builtin_amdgcn_exp2f(pA1[r]);
;   WAIT_BAR(0);
;   DMA_K(3,0);DMA_V(1,SLOTB);
;   ROT();
;   kload8(kf,kp0+sl_cur);
;   WAIT_BAR(3);
.LBB0_309:
	v_mov_b32_e32 v39, s6
	v_add_f32_e32 v39, s5, v39
	v_mul_f32_e32 v40, 0x4f800000, v39
	v_cmp_gt_f32_e32 vcc, s74, v39
	v_add_f32_e32 v37, v37, v38
	v_mul_f32_e32 v38, 0x4f800000, v37
	v_cndmask_b32_e32 v39, v39, v40, vcc
	v_sqrt_f32_e32 v40, v39
	s_waitcnt vmcnt(0) lgkmcnt(0)
	s_barrier
	s_cmp_lg_u32 0, -1
	s_mov_b32 s37, 0
	v_add_u32_e32 v41, -1, v40
	v_fma_f32 v42, -v41, v40, v39
	v_cmp_ge_f32_e64 s[4:5], 0, v42
	v_add_u32_e32 v42, 1, v40
	s_mov_b32 s6, 1
	v_cndmask_b32_e64 v41, v40, v41, s[4:5]
	v_fma_f32 v40, -v42, v40, v39
	v_cmp_lt_f32_e64 s[4:5], 0, v40
	s_nop 1
	v_cndmask_b32_e64 v40, v41, v42, s[4:5]
	v_mul_f32_e32 v41, 0x37800000, v40
	v_cndmask_b32_e32 v40, v40, v41, vcc
	v_cmp_class_f32_e32 vcc, v39, v237
	s_nop 1
	v_cndmask_b32_e32 v39, v40, v39, vcc
	v_cmp_gt_f32_e32 vcc, s74, v37
	v_lshlrev_b32_e32 v40, 1, v36
	v_and_b32_e32 v251, 32, v40
	v_cndmask_b32_e32 v37, v37, v38, vcc
	v_sqrt_f32_e32 v38, v37
	v_lshlrev_b32_e32 v40, 4, v36
	v_and_b32_e32 v40, 0xc0, v40
	v_lshl_or_b32 v246, v242, 8, v40
	v_add_u32_e32 v40, 0, v251
	v_add3_u32 v252, v40, v249, v246
	v_add_u32_e32 v40, -1, v38
	v_fma_f32 v41, -v40, v38, v37
	v_cmp_ge_f32_e64 s[4:5], 0, v41
	v_add_u32_e32 v41, 1, v38
	v_mul_f32_e32 v39, 0x3f8147ae, v39
	v_cndmask_b32_e64 v40, v38, v40, s[4:5]
	v_fma_f32 v38, -v41, v38, v37
	v_cmp_lt_f32_e64 s[4:5], 0, v38
	s_nop 1
	v_cndmask_b32_e64 v38, v40, v41, s[4:5]
	v_mul_f32_e32 v40, 0x37800000, v38
	v_cndmask_b32_e32 v38, v38, v40, vcc
	v_cmp_class_f32_e32 vcc, v37, v237
	s_mov_b64 s[4:5], 0x60000
	s_nop 0
	v_cndmask_b32_e32 v37, v38, v37, vcc
	v_mul_f32_e32 v37, v39, v37
	v_fmamk_f32 v247, v37, 0x3f808312, v238
	v_sub_f32_e32 v0, v0, v247
	v_sub_f32_e32 v1, v1, v247
	v_sub_f32_e32 v16, v16, v247
	v_sub_f32_e32 v17, v17, v247
	v_sub_f32_e32 v2, v2, v247
	v_sub_f32_e32 v18, v18, v247
	s_nop 0
	v_exp_f32_e32 v96, v0
	v_exp_f32_e32 v97, v1
	v_lshl_add_u64 v[0:1], v[32:33], 0, s[4:5]
	s_mov_b32 s4, m0
	s_mov_b32 m0, s3
	s_nop 0
	global_load_lds_dwordx4 v[0:1], off
	s_mov_b32 m0, s4
	s_mov_b64 s[4:5], 0x20000
	v_lshl_add_u64 v[0:1], v[34:35], 0, s[4:5]
	s_cselect_b32 s4, 0, 0
	s_add_i32 s1, s4, s1
	s_add_i32 s4, s1, 0x8000
	s_mov_b32 s5, m0
	s_mov_b32 m0, s4
	s_nop 0
	global_load_lds_dwordx4 v[0:1], off
	s_mov_b32 m0, s5
	s_mov_b64 s[4:5], 0x20080
	v_lshl_add_u64 v[0:1], v[34:35], 0, s[4:5]
	s_add_i32 s1, s1, 0xe000
	s_mov_b32 s4, m0
	s_mov_b32 m0, s1
	s_nop 0
	global_load_lds_dwordx4 v[0:1], off
	s_mov_b32 m0, s4
	ds_read_b128 v[204:207], v250 offset:8192
	ds_read_b128 v[200:203], v250 offset:8704
	ds_read_b128 v[196:199], v250 offset:10240
	ds_read_b128 v[192:195], v250 offset:10752
	ds_read_b128 v[188:191], v250 offset:12288
	ds_read_b128 v[184:187], v250 offset:12800
	ds_read_b128 v[180:183], v250 offset:14336
	ds_read_b128 v[176:179], v250 offset:14848
	v_sub_f32_e32 v3, v3, v247
	v_sub_f32_e32 v19, v19, v247
	v_sub_f32_e32 v4, v4, v247
	v_sub_f32_e32 v20, v20, v247
	v_sub_f32_e32 v5, v5, v247
	v_sub_f32_e32 v21, v21, v247
	v_sub_f32_e32 v6, v6, v247
	v_sub_f32_e32 v22, v22, v247
	v_sub_f32_e32 v7, v7, v247
	v_sub_f32_e32 v23, v23, v247
	v_sub_f32_e32 v8, v8, v247
	v_sub_f32_e32 v24, v24, v247
	v_sub_f32_e32 v9, v9, v247
	v_sub_f32_e32 v25, v25, v247
	v_sub_f32_e32 v10, v10, v247
	v_sub_f32_e32 v26, v26, v247
	v_sub_f32_e32 v11, v11, v247
	v_sub_f32_e32 v27, v27, v247
	v_sub_f32_e32 v12, v12, v247
	v_sub_f32_e32 v28, v28, v247
	v_sub_f32_e32 v13, v13, v247
	v_sub_f32_e32 v29, v29, v247
	v_sub_f32_e32 v14, v14, v247
	v_sub_f32_e32 v30, v30, v247
	v_sub_f32_e32 v15, v15, v247
	v_sub_f32_e32 v31, v31, v247
	v_exp_f32_e32 v98, v2
	v_exp_f32_e32 v99, v3
	v_exp_f32_e32 v100, v4
	v_exp_f32_e32 v101, v5
	v_exp_f32_e32 v102, v6
	v_exp_f32_e32 v103, v7
	v_exp_f32_e32 v104, v8
	v_exp_f32_e32 v105, v9
	v_exp_f32_e32 v106, v10
	v_exp_f32_e32 v107, v11
	v_exp_f32_e32 v108, v12
	v_exp_f32_e32 v109, v13
	v_exp_f32_e32 v110, v14
	v_exp_f32_e32 v111, v15
	v_exp_f32_e32 v80, v16
	v_exp_f32_e32 v81, v17
	v_exp_f32_e32 v82, v18
	v_exp_f32_e32 v83, v19
	v_exp_f32_e32 v84, v20
	v_exp_f32_e32 v85, v21
	v_exp_f32_e32 v86, v22
	v_exp_f32_e32 v87, v23
	v_exp_f32_e32 v88, v24
	v_exp_f32_e32 v89, v25
	v_exp_f32_e32 v90, v26
	v_exp_f32_e32 v91, v27
	v_exp_f32_e32 v92, v28
	v_exp_f32_e32 v93, v29
	v_exp_f32_e32 v94, v30
	v_exp_f32_e32 v95, v31
	s_waitcnt vmcnt(3) lgkmcnt(0)
	s_barrier
	v_and_b32_e32 v0, 3, v36
	s_andn2_b64 vcc, exec, s[54:55]
	v_lshlrev_b32_e32 v208, 4, v0
	s_cbranch_vccnz .LBB0_313
; template<int THRL> __device__ __forceinline__ void attn_unit(int b,int h,int qb,unsigned char*wsb,char*shm,float kmax,const int CMB,float lam){
;     ...
;   float l_reg=0.f;f32x16 o[2];o[0]=f32x16{};o[1]=f32x16{};f32x16 o2[2];o2[0]=f32x16{};o2[1]=f32x16{};const f32x16 negm=f32x16{};
;   const int qrel=wid*QBLK+r32;
;     ...
;   bool resc=false;
;     ...
;   f32x16 pA0,pA1,pB0,pB1;
;   int sl_prev=0,sl_cur=0,sl_next=SLOTB;
	s_lshl_b32 s1, s43, 6
	s_add_i32 s6, s79, s1
	s_lshr_b32 s4, s6, 7
	s_mov_b32 s5, s7
	s_lshl_b64 s[4:5], s[4:5], 8
	s_lshl_b64 s[36:37], s[68:69], 1
	s_add_u32 s4, s36, s4
	v_mov_b32_e32 v209, v221
	s_addc_u32 s5, s37, s5
	s_lshl_b32 s1, s95, 9
	v_lshl_add_u64 v[0:1], s[4:5], 0, v[208:209]
	s_and_b32 s1, s1, 0x18000
	s_lshl_b64 s[4:5], s[66:67], 1
	s_lshl_b64 s[36:37], s[6:7], 1
	v_lshl_or_b32 v2, v214, 11, s1
	s_add_u32 s1, s64, s36
	s_addc_u32 s6, s65, s37
	v_mov_b32_e32 v3, v221
	s_add_u32 s4, s1, s4
	v_lshl_add_u64 v[0:1], v[0:1], 0, v[2:3]
	s_addc_u32 s5, s6, s5
	v_mov_b32_e32 v64, 0
	s_mov_b32 s33, 6
	v_lshl_add_u64 v[210:211], s[64:65], 0, v[0:1]
	v_lshl_add_u64 v[212:213], s[4:5], 0, v[220:221]
	s_movk_i32 s36, 0x4000
	s_movk_i32 s42, 0x2000
	s_mov_b32 s5, 0
	v_mov_b32_e32 v0, 0
	v_mov_b32_e32 v1, v64
	v_mov_b32_e32 v2, v64
	v_mov_b32_e32 v3, v64
	v_mov_b32_e32 v4, v64
	v_mov_b32_e32 v5, v64
	v_mov_b32_e32 v6, v64
	v_mov_b32_e32 v7, v64
	v_mov_b32_e32 v8, v64
	v_mov_b32_e32 v9, v64
	v_mov_b32_e32 v10, v64
	v_mov_b32_e32 v11, v64
	v_mov_b32_e32 v12, v64
	v_mov_b32_e32 v13, v64
	v_mov_b32_e32 v14, v64
	v_mov_b32_e32 v15, v64
	v_mov_b32_e32 v16, 0
	v_mov_b32_e32 v17, v64
	v_mov_b32_e32 v18, v64
	v_mov_b32_e32 v19, v64
	v_mov_b32_e32 v20, v64
	v_mov_b32_e32 v21, v64
	v_mov_b32_e32 v22, v64
	v_mov_b32_e32 v23, v64
	v_mov_b32_e32 v24, v64
	v_mov_b32_e32 v25, v64
	v_mov_b32_e32 v26, v64
	v_mov_b32_e32 v27, v64
	v_mov_b32_e32 v28, v64
	v_mov_b32_e32 v29, v64
	v_mov_b32_e32 v30, v64
	v_mov_b32_e32 v31, v64
	v_mov_b32_e32 v32, 0
	v_mov_b32_e32 v33, v64
	v_mov_b32_e32 v34, v64
	v_mov_b32_e32 v35, v64
	v_mov_b32_e32 v36, v64
	v_mov_b32_e32 v37, v64
	v_mov_b32_e32 v38, v64
	v_mov_b32_e32 v39, v64
	v_mov_b32_e32 v40, v64
	v_mov_b32_e32 v41, v64
	v_mov_b32_e32 v42, v64
	v_mov_b32_e32 v43, v64
	v_mov_b32_e32 v44, v64
	v_mov_b32_e32 v45, v64
	v_mov_b32_e32 v46, v64
	v_mov_b32_e32 v47, v64
	v_mov_b32_e32 v48, 0
	v_mov_b32_e32 v49, v64
	v_mov_b32_e32 v50, v64
	v_mov_b32_e32 v51, v64
	v_mov_b32_e32 v52, v64
	v_mov_b32_e32 v53, v64
	v_mov_b32_e32 v54, v64
	v_mov_b32_e32 v55, v64
	v_mov_b32_e32 v56, v64
	v_mov_b32_e32 v57, v64
	v_mov_b32_e32 v58, v64
	v_mov_b32_e32 v59, v64
	v_mov_b32_e32 v60, v64
	v_mov_b32_e32 v61, v64
	v_mov_b32_e32 v62, v64
	v_mov_b32_e32 v63, v64
	v_lshlrev_b32_e32 v143, 2, v230
	v_add_u32_e32 v143, 0x12800, v143
	ds_write_b32 v143, v246 offset:32768
	ds_write_b32 v143, v230
	ds_write_b32 v143, v231 offset:2048
	ds_write_b32 v143, v232 offset:4096
	ds_write_b32 v143, v233 offset:6144
	ds_write_b32 v143, v234 offset:8192
	ds_write_b32 v143, v235 offset:10240
	ds_write_b32 v143, v236 offset:12288
	ds_write_b32 v143, v237 offset:14336
	ds_write_b32 v143, v238 offset:16384
	ds_write_b32 v143, v239 offset:18432
	ds_write_b32 v143, v240 offset:20480
	ds_write_b32 v143, v241 offset:22528
	ds_write_b32 v143, v242 offset:24576
	ds_write_b32 v143, v243 offset:26624
	ds_write_b32 v143, v244 offset:28672
	ds_write_b32 v143, v245 offset:30720
	v_mov_b32_e32 v246, v143
	v_xor_b32_e32 v230, 0x80000000, v247
	v_mov_b32_e32 v231, v230
	v_mov_b32_e32 v232, v230
	v_mov_b32_e32 v233, v230
	v_mov_b32_e32 v234, v230
	v_mov_b32_e32 v235, v230
	v_mov_b32_e32 v236, v230
	v_mov_b32_e32 v237, v230
	v_mov_b32_e32 v238, v230
	v_mov_b32_e32 v239, v230
	v_mov_b32_e32 v240, v230
	v_mov_b32_e32 v241, v230
	v_mov_b32_e32 v242, v230
	v_mov_b32_e32 v243, v230
	v_mov_b32_e32 v244, v230
	v_mov_b32_e32 v245, v230
	s_waitcnt lgkmcnt(0)
	s_nop 0
	s_nop 0
	s_nop 0
	s_nop 0
	s_nop 0
	s_nop 0
	s_nop 0
	s_nop 0
	s_nop 0
	s_nop 0
.LBB0_311:
	s_mov_b32 s37, s36
	s_mov_b32 s4, s33
	s_mov_b32 s1, s42
	v_add_u32_e32 v209, s5, v252
	ds_read_b64_tr_b16 v[216:217], v209 offset:24576
	ds_read_b64_tr_b16 v[218:219], v209 offset:25088
	v_add_f32_e32 v65, v96, v97
	v_add_f32_e32 v65, v98, v65
	v_add_f32_e32 v65, v99, v65
	v_add_f32_e32 v65, v100, v65
	v_add_f32_e32 v65, v101, v65
	v_cvt_pk_bf16_f32 v172, v96, v97
	v_cvt_pk_bf16_f32 v173, v98, v99
	s_waitcnt lgkmcnt(9)
	v_mfma_f32_32x32x16_bf16 v[128:143], v[204:207], v[156:159], v[230:245]
	ds_read_b64_tr_b16 v[204:205], v209 offset:28672
	ds_read_b64_tr_b16 v[206:207], v209 offset:29184
	v_add_f32_e32 v65, v102, v65
	v_add_f32_e32 v65, v103, v65
	v_add_f32_e32 v65, v104, v65
	v_add_f32_e32 v65, v105, v65
	v_cvt_pk_bf16_f32 v174, v100, v101
	v_cvt_pk_bf16_f32 v175, v102, v103
	s_waitcnt lgkmcnt(10)
	v_mfma_f32_32x32x16_bf16 v[112:127], v[200:203], v[156:159], v[230:245]
	ds_read_b64_tr_b16 v[74:75], v209 offset:25600
	ds_read_b64_tr_b16 v[76:77], v209 offset:26112
	v_add_f32_e32 v65, v106, v65
	v_add_f32_e32 v65, v107, v65
	v_add_f32_e32 v65, v108, v65
	v_add_f32_e32 v65, v109, v65
	v_cvt_pk_bf16_f32 v168, v104, v105
	v_cvt_pk_bf16_f32 v169, v106, v107
	s_waitcnt lgkmcnt(11)
	v_mfma_f32_32x32x16_bf16 v[128:143], v[196:199], v[152:155], v[128:143]
	ds_read_b64_tr_b16 v[70:71], v209 offset:29696
	ds_read_b64_tr_b16 v[72:73], v209 offset:30208
	v_add_f32_e32 v65, v110, v65
	v_add_f32_e32 v65, v111, v65
	v_add_f32_e32 v65, v80, v65
	v_add_f32_e32 v65, v81, v65
	v_cvt_pk_bf16_f32 v170, v108, v109
	v_cvt_pk_bf16_f32 v171, v110, v111
	s_waitcnt lgkmcnt(12)
	v_mfma_f32_32x32x16_bf16 v[112:127], v[192:195], v[152:155], v[112:127]
	ds_read_b64_tr_b16 v[66:67], v209 offset:26624
	ds_read_b64_tr_b16 v[68:69], v209 offset:27136
	v_add_f32_e32 v65, v82, v65
	v_add_f32_e32 v65, v83, v65
	v_add_f32_e32 v65, v84, v65
	v_add_f32_e32 v65, v85, v65
	v_cvt_pk_bf16_f32 v164, v80, v81
	v_cvt_pk_bf16_f32 v165, v82, v83
	s_waitcnt lgkmcnt(13)
	v_mfma_f32_32x32x16_bf16 v[128:143], v[188:191], v[148:151], v[128:143]
	ds_read_b64_tr_b16 v[100:101], v209 offset:30720
	ds_read_b64_tr_b16 v[102:103], v209 offset:31232
	v_add_f32_e32 v65, v86, v65
	v_add_f32_e32 v65, v87, v65
	v_add_f32_e32 v65, v88, v65
	v_add_f32_e32 v65, v89, v65
	v_cvt_pk_bf16_f32 v166, v84, v85
	v_cvt_pk_bf16_f32 v167, v86, v87
	s_waitcnt lgkmcnt(14)
	v_mfma_f32_32x32x16_bf16 v[112:127], v[184:187], v[148:151], v[112:127]
	ds_read_b64_tr_b16 v[96:97], v209 offset:27648
	ds_read_b64_tr_b16 v[98:99], v209 offset:28160
	v_add_f32_e32 v65, v90, v65
	v_add_f32_e32 v65, v91, v65
	v_add_f32_e32 v65, v92, v65
	v_add_f32_e32 v65, v93, v65
	v_cvt_pk_bf16_f32 v160, v88, v89
	v_cvt_pk_bf16_f32 v161, v90, v91
	s_waitcnt lgkmcnt(14)
	v_mfma_f32_32x32x16_bf16 v[128:143], v[180:183], v[144:147], v[128:143]
	ds_read_b64_tr_b16 v[86:87], v209 offset:31744
	ds_read_b64_tr_b16 v[88:89], v209 offset:32256
	v_add_f32_e32 v65, v94, v65
	v_add_f32_e32 v65, v95, v65
	v_add_f32_e32 v65, 0, v65
	v_cvt_pk_bf16_f32 v162, v92, v93
	v_cvt_pk_bf16_f32 v163, v94, v95
	v_mfma_f32_32x32x16_bf16 v[112:127], v[176:179], v[144:147], v[112:127]
	v_lshl_add_u64 v[190:191], v[212:213], 0, s[48:49]
	v_lshl_add_u64 v[78:79], v[190:191], 0, s[10:11]
	s_add_i32 s5, s42, s3
	s_mov_b32 s6, m0
	s_mov_b32 m0, s5
	s_nop 0
	global_load_lds_dwordx4 v[78:79], off
	s_mov_b32 m0, s6
	v_lshl_add_u64 v[188:189], v[210:211], 0, s[48:49]
	v_lshl_add_u64 v[78:79], v[188:189], 0, s[12:13]
	s_add_i32 s5, s36, s97
	s_mov_b32 s6, m0
	s_mov_b32 m0, s5
	s_nop 0
	global_load_lds_dwordx4 v[78:79], off
	s_mov_b32 m0, s6
	v_lshl_add_u64 v[78:79], v[188:189], 0, s[14:15]
	s_add_i32 s5, s36, s96
	s_mov_b32 s6, m0
	s_mov_b32 m0, s5
	s_nop 0
	global_load_lds_dwordx4 v[78:79], off
	s_mov_b32 m0, s6
	s_waitcnt lgkmcnt(14)
	v_mfma_f32_32x32x16_bf16 v[32:47], v[172:175], v[216:219], v[32:47]
	v_exp_f32_e32 v128, v128
	v_exp_f32_e32 v129, v129
	ds_read_b64_tr_b16 v[90:91], v209 offset:49152
	ds_read_b64_tr_b16 v[92:93], v209 offset:49664
	s_waitcnt lgkmcnt(14)
	v_mfma_f32_32x32x16_bf16 v[48:63], v[172:175], v[204:207], v[48:63]
	v_exp_f32_e32 v130, v130
	v_exp_f32_e32 v131, v131
	ds_read_b64_tr_b16 v[104:105], v209 offset:53248
	ds_read_b64_tr_b16 v[106:107], v209 offset:53760
	v_add_u32_e32 v94, s37, v250
	ds_read_b128 v[82:85], v94
	ds_read_b128 v[78:81], v94 offset:512
	s_waitcnt lgkmcnt(14)
	v_mfma_f32_32x32x16_bf16 v[32:47], v[168:171], v[74:77], v[32:47]
	v_exp_f32_e32 v132, v132
	v_exp_f32_e32 v133, v133
	ds_read_b64_tr_b16 v[108:109], v209 offset:50176
	ds_read_b64_tr_b16 v[110:111], v209 offset:50688
	ds_read_b128 v[184:187], v94 offset:2048
	ds_read_b128 v[176:179], v94 offset:2560
	v_mfma_f32_32x32x16_bf16 v[48:63], v[168:171], v[70:73], v[48:63]
	v_exp_f32_e32 v134, v134
	v_exp_f32_e32 v135, v135
	ds_read_b64_tr_b16 v[192:193], v209 offset:54272
	ds_read_b64_tr_b16 v[194:195], v209 offset:54784
	ds_read_b128 v[180:183], v94 offset:4096
	ds_read_b128 v[70:73], v94 offset:4608
	s_waitcnt lgkmcnt(14)
	v_mfma_f32_32x32x16_bf16 v[32:47], v[164:167], v[66:69], v[32:47]
	v_exp_f32_e32 v136, v136
	v_exp_f32_e32 v137, v137
	ds_read_b64_tr_b16 v[196:197], v209 offset:51200
	ds_read_b64_tr_b16 v[198:199], v209 offset:51712
	ds_read_b128 v[74:77], v94 offset:6144
	ds_read_b128 v[66:69], v94 offset:6656
	v_mfma_f32_32x32x16_bf16 v[48:63], v[164:167], v[100:103], v[48:63]
	v_exp_f32_e32 v138, v138
	v_exp_f32_e32 v139, v139
	ds_read_b64_tr_b16 v[100:101], v209 offset:55296
	ds_read_b64_tr_b16 v[102:103], v209 offset:55808
	v_mfma_f32_32x32x16_bf16 v[32:47], v[160:163], v[96:99], v[32:47]
	v_exp_f32_e32 v140, v140
	v_exp_f32_e32 v141, v141
	ds_read_b64_tr_b16 v[94:95], v209 offset:52224
	ds_read_b64_tr_b16 v[96:97], v209 offset:52736
	v_mfma_f32_32x32x16_bf16 v[48:63], v[160:163], v[86:89], v[48:63]
	v_exp_f32_e32 v142, v142
	v_exp_f32_e32 v143, v143
	ds_read_b64_tr_b16 v[86:87], v209 offset:56320
	ds_read_b64_tr_b16 v[88:89], v209 offset:56832
	s_waitcnt lgkmcnt(14)
	v_mfma_f32_32x32x16_bf16 v[0:15], v[172:175], v[90:93], v[0:15]
	v_exp_f32_e32 v112, v112
	v_exp_f32_e32 v113, v113
	v_mfma_f32_32x32x16_bf16 v[16:31], v[172:175], v[104:107], v[16:31]
	v_exp_f32_e32 v114, v114
	v_exp_f32_e32 v115, v115
	v_mfma_f32_32x32x16_bf16 v[0:15], v[168:171], v[108:111], v[0:15]
	v_exp_f32_e32 v116, v116
	v_exp_f32_e32 v117, v117
	s_waitcnt lgkmcnt(12)
	v_mfma_f32_32x32x16_bf16 v[16:31], v[168:171], v[192:195], v[16:31]
	v_exp_f32_e32 v118, v118
	v_exp_f32_e32 v119, v119
	s_waitcnt lgkmcnt(8)
	v_mfma_f32_32x32x16_bf16 v[0:15], v[164:167], v[196:199], v[0:15]
	v_exp_f32_e32 v120, v120
	v_exp_f32_e32 v121, v121
	s_waitcnt lgkmcnt(4)
	v_mfma_f32_32x32x16_bf16 v[16:31], v[164:167], v[100:103], v[16:31]
	v_exp_f32_e32 v122, v122
	v_exp_f32_e32 v123, v123
	s_waitcnt lgkmcnt(2)
	v_mfma_f32_32x32x16_bf16 v[0:15], v[160:163], v[94:97], v[0:15]
	v_exp_f32_e32 v124, v124
	v_exp_f32_e32 v125, v125
	s_waitcnt lgkmcnt(0)
	v_mfma_f32_32x32x16_bf16 v[16:31], v[160:163], v[86:89], v[16:31]
	v_exp_f32_e32 v126, v126
	v_exp_f32_e32 v127, v127
	s_waitcnt vmcnt(3) lgkmcnt(0)
	s_barrier
; #define WAIT_BAR(N) asm volatile("s_waitcnt vmcnt(" #N ") lgkmcnt(0)\n\ts_barrier":::"memory")
;   #define RESC() do{ if(resc){ asm volatile("s_waitcnt lgkmcnt(0)":::"memory"); \
;       _Pragma("unroll") for(int d_=0;d_<2;++d_) _Pragma("unroll") for(int r=0;r<16;++r){const float f_=wsf[crow(r,hi)];o[d_][r]*=f_;o2[d_][r]*=f_;} } }while(0)
;   #define ROT() do{sl_prev=sl_cur;sl_cur=sl_next;sl_next=(sl_next==(NSLOT-1)*SLOTB)?0:sl_next+SLOTB;}while(0)
; template<int THRL> __device__ __forceinline__ void attn_unit(int b,int h,int qb,unsigned char*wsb,char*shm,float kmax,const int CMB,float lam){
;     ...
;   int t=1;
;     ...
;   for(;t+5<NT;t+=2){
;     STEP(pB0,pB1,pA0,pA1,t,true,true,true);     WAIT_BAR(3); RESC(); ROT();
;     STEP(pA0,pA1,pB0,pB1,t+1,true,true,true);   WAIT_BAR(3); RESC(); ROT();
	s_add_i32 s5, s36, 0x2000
	s_cmpk_lg_i32 s36, 0x4000
	s_cselect_b32 s42, s5, 0
	v_add_u32_e32 v209, s1, v252
	ds_read_b64_tr_b16 v[192:193], v209 offset:24576
	ds_read_b64_tr_b16 v[194:195], v209 offset:25088
	v_mfma_f32_32x32x16_bf16 v[96:111], v[82:85], v[156:159], v[230:245]
	v_add_f32_e32 v86, v128, v129
	v_add_f32_e32 v86, v130, v86
	v_add_f32_e32 v86, v131, v86
	v_add_f32_e32 v86, v132, v86
	v_add_f32_e32 v86, v133, v86
	v_cvt_pk_bf16_f32 v172, v128, v129
	v_cvt_pk_bf16_f32 v173, v130, v131
	ds_read_b64_tr_b16 v[196:197], v209 offset:28672
	ds_read_b64_tr_b16 v[198:199], v209 offset:29184
	v_add_f32_e32 v82, v134, v86
	v_add_f32_e32 v82, v135, v82
	v_add_f32_e32 v82, v136, v82
	v_add_f32_e32 v128, v137, v82
	v_mfma_f32_32x32x16_bf16 v[80:95], v[78:81], v[156:159], v[230:245]
	v_cvt_pk_bf16_f32 v174, v132, v133
	v_cvt_pk_bf16_f32 v175, v134, v135
	ds_read_b64_tr_b16 v[216:217], v209 offset:25600
	ds_read_b64_tr_b16 v[218:219], v209 offset:26112
	v_mfma_f32_32x32x16_bf16 v[96:111], v[184:187], v[152:155], v[96:111]
	v_add_f32_e32 v78, v138, v128
	v_add_f32_e32 v78, v139, v78
	v_add_f32_e32 v78, v140, v78
	v_add_f32_e32 v78, v141, v78
	v_cvt_pk_bf16_f32 v168, v136, v137
	v_cvt_pk_bf16_f32 v169, v138, v139
	ds_read_b64_tr_b16 v[136:137], v209 offset:29696
	ds_read_b64_tr_b16 v[138:139], v209 offset:30208
	v_mfma_f32_32x32x16_bf16 v[80:95], v[176:179], v[152:155], v[80:95]
	v_add_f32_e32 v78, v142, v78
	v_add_f32_e32 v78, v143, v78
	v_add_f32_e32 v78, v112, v78
	v_add_f32_e32 v78, v113, v78
	v_cvt_pk_bf16_f32 v170, v140, v141
	v_cvt_pk_bf16_f32 v171, v142, v143
	ds_read_b64_tr_b16 v[132:133], v209 offset:26624
	ds_read_b64_tr_b16 v[134:135], v209 offset:27136
	v_mfma_f32_32x32x16_bf16 v[96:111], v[180:183], v[148:151], v[96:111]
	v_add_f32_e32 v78, v114, v78
	v_add_f32_e32 v78, v115, v78
	v_add_f32_e32 v78, v116, v78
	v_add_f32_e32 v78, v117, v78
	v_cvt_pk_bf16_f32 v164, v112, v113
	v_cvt_pk_bf16_f32 v165, v114, v115
	ds_read_b64_tr_b16 v[128:129], v209 offset:30720
	ds_read_b64_tr_b16 v[130:131], v209 offset:31232
	v_mfma_f32_32x32x16_bf16 v[80:95], v[70:73], v[148:151], v[80:95]
	v_add_f32_e32 v78, v118, v78
	v_add_f32_e32 v78, v119, v78
	v_add_f32_e32 v78, v120, v78
	v_add_f32_e32 v78, v121, v78
	v_cvt_pk_bf16_f32 v166, v116, v117
	v_cvt_pk_bf16_f32 v167, v118, v119
	ds_read_b64_tr_b16 v[112:113], v209 offset:27648
	ds_read_b64_tr_b16 v[114:115], v209 offset:28160
	v_mfma_f32_32x32x16_bf16 v[96:111], v[74:77], v[144:147], v[96:111]
	v_add_f32_e32 v70, v122, v78
	v_add_f32_e32 v70, v123, v70
	v_add_f32_e32 v70, v124, v70
	v_add_f32_e32 v78, v125, v70
	v_cvt_pk_bf16_f32 v160, v120, v121
	v_cvt_pk_bf16_f32 v161, v122, v123
	ds_read_b64_tr_b16 v[70:71], v209 offset:31744
	ds_read_b64_tr_b16 v[72:73], v209 offset:32256
	v_mfma_f32_32x32x16_bf16 v[80:95], v[66:69], v[144:147], v[80:95]
	v_add_f32_e32 v74, v126, v78
	v_add_f32_e32 v74, v127, v74
	v_add_f32_e32 v74, 0, v74
	v_cvt_pk_bf16_f32 v162, v124, v125
	v_cvt_pk_bf16_f32 v163, v126, v127
	v_lshl_add_u64 v[66:67], v[190:191], 0, s[16:17]
	s_add_i32 s1, s36, s3
	s_mov_b32 s5, m0
	s_mov_b32 m0, s1
	s_nop 0
	global_load_lds_dwordx4 v[66:67], off
	s_mov_b32 m0, s5
	v_lshl_add_u64 v[66:67], v[188:189], 0, s[18:19]
	s_add_i32 s1, s42, s97
	s_mov_b32 s5, m0
	s_mov_b32 m0, s1
	s_nop 0
	global_load_lds_dwordx4 v[66:67], off
	s_mov_b32 m0, s5
	v_lshl_add_u64 v[66:67], v[188:189], 0, s[20:21]
	s_add_i32 s1, s42, s96
	s_mov_b32 s5, m0
	s_mov_b32 m0, s1
	s_nop 0
	global_load_lds_dwordx4 v[66:67], off
	s_mov_b32 m0, s5
	s_waitcnt lgkmcnt(14)
	v_mfma_f32_32x32x16_bf16 v[32:47], v[172:175], v[192:195], v[32:47]
	v_exp_f32_e32 v96, v96
	v_exp_f32_e32 v97, v97
	ds_read_b64_tr_b16 v[66:67], v209 offset:49152
	ds_read_b64_tr_b16 v[68:69], v209 offset:49664
	s_waitcnt lgkmcnt(14)
	v_mfma_f32_32x32x16_bf16 v[48:63], v[172:175], v[196:199], v[48:63]
	v_exp_f32_e32 v98, v98
	v_exp_f32_e32 v99, v99
	ds_read_b64_tr_b16 v[76:77], v209 offset:53248
	ds_read_b64_tr_b16 v[78:79], v209 offset:53760
	v_add_u32_e32 v75, s42, v250
	ds_read_b128 v[204:207], v75
	ds_read_b128 v[200:203], v75 offset:512
	s_waitcnt lgkmcnt(14)
	v_mfma_f32_32x32x16_bf16 v[32:47], v[168:171], v[216:219], v[32:47]
	v_exp_f32_e32 v100, v100
	v_exp_f32_e32 v101, v101
	ds_read_b64_tr_b16 v[116:117], v209 offset:50176
	ds_read_b64_tr_b16 v[118:119], v209 offset:50688
	ds_read_b128 v[196:199], v75 offset:2048
	ds_read_b128 v[192:195], v75 offset:2560
	v_mfma_f32_32x32x16_bf16 v[48:63], v[168:171], v[136:139], v[48:63]
	v_exp_f32_e32 v102, v102
	v_exp_f32_e32 v103, v103
	ds_read_b64_tr_b16 v[120:121], v209 offset:54272
	ds_read_b64_tr_b16 v[122:123], v209 offset:54784
	ds_read_b128 v[188:191], v75 offset:4096
	ds_read_b128 v[184:187], v75 offset:4608
	s_waitcnt lgkmcnt(14)
	v_mfma_f32_32x32x16_bf16 v[32:47], v[164:167], v[132:135], v[32:47]
	v_exp_f32_e32 v104, v104
	v_exp_f32_e32 v105, v105
	ds_read_b64_tr_b16 v[124:125], v209 offset:51200
	ds_read_b64_tr_b16 v[126:127], v209 offset:51712
	ds_read_b128 v[180:183], v75 offset:6144
	ds_read_b128 v[176:179], v75 offset:6656
	v_mfma_f32_32x32x16_bf16 v[48:63], v[164:167], v[128:131], v[48:63]
	v_exp_f32_e32 v106, v106
	v_exp_f32_e32 v107, v107
	ds_read_b64_tr_b16 v[128:129], v209 offset:55296
	ds_read_b64_tr_b16 v[130:131], v209 offset:55808
	v_mfma_f32_32x32x16_bf16 v[32:47], v[160:163], v[112:115], v[32:47]
	v_exp_f32_e32 v108, v108
	v_exp_f32_e32 v109, v109
	ds_read_b64_tr_b16 v[112:113], v209 offset:52224
	ds_read_b64_tr_b16 v[114:115], v209 offset:52736
	v_mfma_f32_32x32x16_bf16 v[48:63], v[160:163], v[70:73], v[48:63]
	v_exp_f32_e32 v110, v110
	v_exp_f32_e32 v111, v111
	ds_read_b64_tr_b16 v[70:71], v209 offset:56320
	ds_read_b64_tr_b16 v[72:73], v209 offset:56832
	s_waitcnt lgkmcnt(14)
	v_mfma_f32_32x32x16_bf16 v[0:15], v[172:175], v[66:69], v[0:15]
	v_exp_f32_e32 v80, v80
	v_exp_f32_e32 v81, v81
	v_mfma_f32_32x32x16_bf16 v[16:31], v[172:175], v[76:79], v[16:31]
	v_exp_f32_e32 v82, v82
	v_exp_f32_e32 v83, v83
	v_mfma_f32_32x32x16_bf16 v[0:15], v[168:171], v[116:119], v[0:15]
	v_exp_f32_e32 v84, v84
	v_exp_f32_e32 v85, v85
	s_waitcnt lgkmcnt(12)
	v_mfma_f32_32x32x16_bf16 v[16:31], v[168:171], v[120:123], v[16:31]
	v_exp_f32_e32 v86, v86
	v_exp_f32_e32 v87, v87
	s_waitcnt lgkmcnt(8)
	v_mfma_f32_32x32x16_bf16 v[0:15], v[164:167], v[124:127], v[0:15]
	v_exp_f32_e32 v88, v88
	v_exp_f32_e32 v89, v89
	s_waitcnt lgkmcnt(4)
	v_mfma_f32_32x32x16_bf16 v[16:31], v[164:167], v[128:131], v[16:31]
	v_exp_f32_e32 v90, v90
	v_exp_f32_e32 v91, v91
	s_waitcnt lgkmcnt(2)
	v_mfma_f32_32x32x16_bf16 v[0:15], v[160:163], v[112:115], v[0:15]
	v_exp_f32_e32 v92, v92
	v_exp_f32_e32 v93, v93
	s_waitcnt lgkmcnt(0)
	v_mfma_f32_32x32x16_bf16 v[16:31], v[160:163], v[70:73], v[16:31]
	v_exp_f32_e32 v94, v94
	v_exp_f32_e32 v95, v95
	s_add_i32 s1, s42, 0x2000
	s_waitcnt vmcnt(3) lgkmcnt(0)
	s_barrier
; #define WAIT_BAR(N) asm volatile("s_waitcnt vmcnt(" #N ") lgkmcnt(0)\n\ts_barrier":::"memory")
;   #define RESC() do{ if(resc){ asm volatile("s_waitcnt lgkmcnt(0)":::"memory"); \
;       _Pragma("unroll") for(int d_=0;d_<2;++d_) _Pragma("unroll") for(int r=0;r<16;++r){const float f_=wsf[crow(r,hi)];o[d_][r]*=f_;o2[d_][r]*=f_;} } }while(0)
;   #define ROT() do{sl_prev=sl_cur;sl_cur=sl_next;sl_next=(sl_next==(NSLOT-1)*SLOTB)?0:sl_next+SLOTB;}while(0)
;   #define ENDW(tt) do{ if((tt)+3<NT){WAIT_BAR(3);} else if((tt)+2<NT){WAIT_BAR(2);} else {WAIT_BAR(0);} }while(0)
; template<int THRL> __device__ __forceinline__ void attn_unit(int b,int h,int qb,unsigned char*wsb,char*shm,float kmax,const int CMB,float lam){
;     ...
;   for(;t+5<NT;t+=2){
;     STEP(pB0,pB1,pA0,pA1,t,true,true,true);     WAIT_BAR(3); RESC(); ROT();
;     STEP(pA0,pA1,pB0,pB1,t+1,true,true,true);   WAIT_BAR(3); RESC(); ROT();
;   }
;     ...
;   for(;t+1<NT;t+=2){
;     STEP(pB0,pB1,pA0,pA1,t,(t+3<NT),(t+1<NT),(t+1<NT));       ENDW(t);   RESC(); ROT();
;     STEP(pA0,pA1,pB0,pB1,t+1,(t+4<NT),(t+2<NT),(t+2<NT));     ENDW(t+1); RESC(); ROT();
;   }
	s_cmpk_lg_i32 s42, 0x4000
	v_add_f32_e32 v64, v64, v65
	s_mov_b32 s5, s36
	s_cselect_b32 s36, s1, 0
	s_add_i32 s33, s33, 2
	v_lshl_add_u64 v[210:211], v[210:211], 0, s[22:23]
	v_lshl_add_u64 v[212:213], v[212:213], 0, s[22:23]
	s_cmp_ge_u32 s33, s89
	v_add_f32_e32 v64, v64, v74
	s_cbranch_scc0 .LBB0_311
	ds_read_b32 v230, v246
	ds_read_b32 v231, v246 offset:2048
	ds_read_b32 v232, v246 offset:4096
	ds_read_b32 v233, v246 offset:6144
	ds_read_b32 v234, v246 offset:8192
	ds_read_b32 v235, v246 offset:10240
	ds_read_b32 v236, v246 offset:12288
	ds_read_b32 v237, v246 offset:14336
	ds_read_b32 v238, v246 offset:16384
	ds_read_b32 v239, v246 offset:18432
	ds_read_b32 v240, v246 offset:20480
	ds_read_b32 v241, v246 offset:22528
	ds_read_b32 v242, v246 offset:24576
	ds_read_b32 v243, v246 offset:26624
	ds_read_b32 v244, v246 offset:28672
	ds_read_b32 v245, v246 offset:30720
	ds_read_b32 v246, v246 offset:32768
	s_waitcnt lgkmcnt(0)
	s_nop 0
	s_nop 0
	s_nop 0
	s_nop 0
	s_nop 0
	s_nop 0
	s_add_i32 s6, s4, -3
	s_branch .LBB0_314
